# MLA fixed-shift loop unrolled by two with swapped score registers: the 8 v_mov_b64 per tile removed
# baseline (speedup 1.0000x reference)
.LBB0_1187:
	s_or_b64 exec, exec, s[36:37]
	s_add_i32 s34, s34, 1
	s_bitcmp1_b32 s34, 0
	s_cselect_b32 s36, 0x3400, 0
	v_add_u32_e32 v112, s36, v180
	ds_read_b128 v[132:135], v112
	ds_read_b128 v[136:139], v112 offset:32
	v_exp_f32_e32 v174, v48
	v_exp_f32_e32 v175, v49
	v_exp_f32_e32 v182, v50
	s_waitcnt lgkmcnt(0)
	v_mfma_f32_32x32x16_bf16 v[80:95], v[132:135], v[100:103], v[32:47]
	v_exp_f32_e32 v183, v51
	v_exp_f32_e32 v184, v52
	v_exp_f32_e32 v185, v53
	v_exp_f32_e32 v186, v54
	v_exp_f32_e32 v187, v55
	v_exp_f32_e32 v188, v56
	v_exp_f32_e32 v189, v57
	v_mfma_f32_32x32x16_bf16 v[80:95], v[136:139], v[104:107], v[80:95]
	ds_read_b128 v[132:135], v112 offset:64
	ds_read_b128 v[136:139], v112 offset:96
	v_exp_f32_e32 v190, v58
	v_exp_f32_e32 v191, v59
	v_exp_f32_e32 v192, v60
	v_exp_f32_e32 v193, v61
	v_exp_f32_e32 v194, v62
	v_exp_f32_e32 v195, v63
	s_waitcnt lgkmcnt(0)
	v_mfma_f32_32x32x16_bf16 v[80:95], v[132:135], v[108:111], v[80:95]
	ds_read_b128 v[132:135], v112 offset:128
	ds_read_b128 v[48:51], v112 offset:160
	s_and_b64 s[18:19], s[18:19], exec
	s_cselect_b32 s18, 0x2400, 0
	v_exp_f32_e32 v198, v64
	v_exp_f32_e32 v199, v65
	v_exp_f32_e32 v200, v70
	v_mfma_f32_32x32x16_bf16 v[80:95], v[136:139], v[116:119], v[80:95]
	v_exp_f32_e32 v201, v71
	v_exp_f32_e32 v202, v72
	v_exp_f32_e32 v203, v73
	v_exp_f32_e32 v76, v76
	v_cvt_pk_bf16_f32 v71, v200, v201
	v_exp_f32_e32 v78, v78
	v_exp_f32_e32 v79, v79
	s_waitcnt lgkmcnt(0)
	v_mfma_f32_32x32x16_bf16 v[80:95], v[132:135], v[120:123], v[80:95]
	ds_read_b128 v[132:135], v112 offset:6656
	ds_read_b128 v[146:149], v112 offset:6688
	v_exp_f32_e32 v77, v77
	v_cmp_eq_u32_e32 vcc, s34, v173
	v_lshl_add_u64 v[142:143], v[142:143], 0, s[24:25]
	v_lshl_add_u64 v[162:163], v[162:163], 0, s[24:25]
	s_or_b64 s[2:3], vcc, s[2:3]
	v_mfma_f32_32x32x16_bf16 v[80:95], v[48:51], v[96:99], v[80:95]
	s_waitcnt lgkmcnt(0)
	v_mfma_f32_32x32x16_bf16 v[48:63], v[132:135], v[100:103], v[32:47]
	global_load_dwordx4 v[132:135], v[164:165], off
	ds_read_b128 v[150:153], v112 offset:6720
	ds_read_b128 v[154:157], v112 offset:6752
	ds_read_b128 v[158:161], v112 offset:6784
	ds_read_b128 v[136:139], v112 offset:6816
	v_add_u32_e32 v112, s18, v179
	v_lshl_add_u64 v[164:165], v[164:165], 0, s[0:1]
	v_mfma_f32_32x32x16_bf16 v[48:63], v[146:149], v[104:107], v[48:63]
	v_exp_f32_e32 v146, v66
	v_exp_f32_e32 v147, v67
	v_exp_f32_e32 v148, v68
	v_exp_f32_e32 v149, v69
	ds_read_b64_tr_b16 v[64:65], v112 offset:26624
	ds_read_b64_tr_b16 v[66:67], v112 offset:27776
	v_cvt_pk_bf16_f32 v68, v198, v199
	v_cvt_pk_bf16_f32 v69, v146, v147
	s_waitcnt lgkmcnt(0)
	v_mfma_f32_32x32x16_bf16 v[48:63], v[150:153], v[108:111], v[48:63]
	v_exp_f32_e32 v150, v74
	v_exp_f32_e32 v151, v75
	ds_read_b64_tr_b16 v[74:75], v112 offset:27840
	ds_read_b64_tr_b16 v[72:73], v112 offset:26688
	v_cvt_pk_bf16_f32 v70, v148, v149
	v_pk_add_f32 v[146:147], v[182:183], v[146:147]
	v_pk_add_f32 v[198:199], v[174:175], v[198:199]
	v_pk_add_f32 v[148:149], v[184:185], v[148:149]
	v_mfma_f32_32x32x16_bf16 v[0:15], v[64:67], v[68:71], v[0:15]
	ds_read_b64_tr_b16 v[64:65], v112 offset:28928
	ds_read_b64_tr_b16 v[66:67], v112 offset:30080
	v_add_f32_e64 v152, v194, v78
	v_add_f32_e64 v153, v195, v79
	s_waitcnt lgkmcnt(0)
	v_mfma_f32_32x32x16_bf16 v[16:31], v[72:75], v[68:71], v[16:31]
	ds_read_b64_tr_b16 v[74:75], v112 offset:30144
	ds_read_b64_tr_b16 v[72:73], v112 offset:28992
	v_cvt_pk_bf16_f32 v68, v202, v203
	v_cvt_pk_bf16_f32 v69, v150, v151
	v_cvt_pk_bf16_f32 v70, v76, v77
	v_cvt_pk_bf16_f32 v71, v78, v79
	v_mfma_f32_32x32x16_bf16 v[48:63], v[154:157], v[116:119], v[48:63]
	v_add_f32_e64 v154, v192, v76
	v_add_f32_e64 v155, v193, v77
	v_add_f32_e64 v156, v190, v150
	v_add_f32_e64 v157, v191, v151
	v_mfma_f32_32x32x16_bf16 v[0:15], v[64:67], v[68:71], v[0:15]
	s_waitcnt lgkmcnt(0)
	v_mfma_f32_32x32x16_bf16 v[16:31], v[72:75], v[68:71], v[16:31]
	v_cvt_pk_bf16_f32 v68, v174, v175
	v_cvt_pk_bf16_f32 v69, v182, v183
	v_cvt_pk_bf16_f32 v70, v184, v185
	v_cvt_pk_bf16_f32 v71, v186, v187
	v_mfma_f32_32x32x16_bf16 v[48:63], v[158:161], v[120:123], v[48:63]
	v_add_f32_e64 v160, v186, v200
	v_add_f32_e64 v161, v187, v201
	v_pk_mov_b32 v[200:201], v[198:199], v[146:147] op_sel:[1,0]
	v_mov_b32_e32 v199, v147
	v_pk_add_f32 v[64:65], v[200:201], v[198:199]
	v_pk_mov_b32 v[78:79], v[148:149], v[160:161] op_sel:[1,0]
	v_pk_add_f32 v[76:77], v[64:65], v[64:65] op_sel_hi:[0,1]
	ds_read_b64_tr_b16 v[64:65], v112 offset:31232
	ds_read_b64_tr_b16 v[66:67], v112 offset:32384
	ds_read_b64_tr_b16 v[74:75], v112 offset:32448
	ds_read_b64_tr_b16 v[72:73], v112 offset:31296
	s_waitcnt lgkmcnt(0)
	v_mfma_f32_32x32x16_bf16 v[0:15], v[64:67], v[68:71], v[0:15]
	ds_read_b64_tr_b16 v[64:65], v112 offset:33536
	ds_read_b64_tr_b16 v[66:67], v112 offset:34688
	v_mov_b32_e32 v149, v161
	v_add_f32_e64 v78, v78, v148
	v_add_f32_e64 v79, v79, v149
	v_pk_add_f32 v[158:159], v[188:189], v[202:203]
	v_pk_add_f32 v[78:79], v[78:79], v[78:79] op_sel_hi:[0,1]
	v_add_f32_e32 v147, v158, v159
	v_add_f32_e32 v149, v156, v157
	v_mfma_f32_32x32x16_bf16 v[16:31], v[72:75], v[68:71], v[16:31]
	ds_read_b64_tr_b16 v[74:75], v112 offset:34752
	ds_read_b64_tr_b16 v[72:73], v112 offset:33600
	v_cvt_pk_bf16_f32 v68, v188, v189
	v_cvt_pk_bf16_f32 v69, v190, v191
	v_cvt_pk_bf16_f32 v70, v192, v193
	v_cvt_pk_bf16_f32 v71, v194, v195
	v_mov_b32_e32 v146, v154
	v_mov_b32_e32 v148, v155
	s_waitcnt lgkmcnt(0)
	v_mfma_f32_32x32x16_bf16 v[0:15], v[64:67], v[68:71], v[0:15]
	v_mov_b32_e32 v76, v152
	v_mov_b32_e32 v78, v153
	v_add_f32_e64 v146, v146, v148
	v_add_f32_e64 v147, v147, v149
	v_add_f32_e64 v64, v76, v78
	v_add_f32_e64 v65, v77, v79
	v_pk_add_f32 v[64:65], v[146:147], v[64:65]
	s_barrier
	v_mfma_f32_32x32x16_bf16 v[16:31], v[72:75], v[68:71], v[16:31]
	v_add_f32_e32 v64, v64, v65
	v_add_f32_e32 v114, v114, v64
	v_mfma_f32_32x32x16_bf16 v[48:63], v[136:139], v[96:99], v[48:63]
	s_andn2_b64 exec, exec, s[2:3]
	s_cbranch_execz .Lmla_exit_e
.Lmla_top_o:
	s_bitcmp1_b32 s34, 0
	s_cselect_b64 s[18:19], -1, 0
	s_and_b64 s[36:37], s[18:19], exec
	s_cselect_b32 s36, 0x3400, 0
	s_add_i32 s46, s36, 0
	v_add3_u32 v112, s46, v168, v170
	s_waitcnt vmcnt(0)
	ds_write_b128 v112, v[128:131]
	s_and_saveexec_b64 s[36:37], s[6:7]
	v_add3_u32 v112, s46, v171, v172
	ds_write_b128 v112, v[124:127]
	s_or_b64 exec, exec, s[36:37]
	s_andn2_b32 s36, 1, s34
	s_mulk_i32 s36, 0x2400
	v_add_u32_e32 v112, s36, v115
	ds_write_b128 v112, v[132:135] offset:26624
	global_load_dwordx4 v[128:131], v[162:163], off
	s_and_saveexec_b64 s[36:37], s[6:7]
	s_cbranch_execz .Lmla_body_o
	global_load_dwordx4 v[124:127], v[142:143], off
	s_branch .Lmla_body_o
